# k20 + attn_pv + attn_depk + filt_pipe v2 combined
# speedup vs baseline: 1.0027x; 1.0027x over previous
; __device__ void phase_attn(const Params& p, unsigned char* smem, int wave) {
;     ...
;         const bf16x8 qf0 = *(const bf16x8*)(Qs + (16 * w4 + ql) * ATT_LD + gq * 8), qf1 = *(const bf16x8*)(Qs + (16 * w4 + ql) * ATT_LD + 32 + gq * 8);
;         f32x4 sc[10];
; #pragma unroll
;         for (int kt = 0; kt < 9; ++kt) { const bf16_t* kr = Ks + (16 * w4 + 16 * kt + ql) * ATT_LD + gq * 8;
;             f32x4 a = (f32x4){0.f, 0.f, 0.f, 0.f};
;             a = __builtin_amdgcn_mfma_f32_16x16x32_bf16(*(const bf16x8*)kr, qf0, a, 0, 0, 0);
;             a = __builtin_amdgcn_mfma_f32_16x16x32_bf16(*(const bf16x8*)(kr + 32), qf1, a, 0, 0, 0);
;             sc[kt] = a; if (kt % 3 == 2) __builtin_amdgcn_sched_barrier(0); }
;         const float slope = exp2f(-(float)(h + 1)) * (float)d * 1.4426950408889634f;
;         const int qi = i0 + 16 * w4 + ql;
;         float mx = -1e30f;
; #pragma unroll
;         for (int kt = 0; kt < 9; ++kt)
; #pragma unroll
;             for (int j = 0; j < 4; ++j) { const int rel = 16 * kt + 4 * gq + j - 64 - ql; const int jk = qi + rel;
;                 const bool relok = (kt == 0) ? (rel >= -64) : ((kt == 8) ? (rel <= 64) : true);
;                 const bool ok = relok && ((unsigned)jk < (unsigned)Ls);
;                 const float v = ok ? sc[kt][j] * 0.18033688011112042f - slope * fabsf((float)rel) : -1e30f;
;                 sc[kt][j] = v; mx = fmaxf(mx, v); }
.LBB0_732:
	ds_read_b128 v[46:49], v140 offset:18432
	ds_read_b128 v[186:189], v140
	ds_read_b128 v[50:53], v140 offset:18496
	ds_read_b128 v[190:193], v140 offset:64
	ds_read_b128 v[54:57], v140 offset:20736
	ds_read_b128 v[58:61], v140 offset:20800
	v_readlane_b32 s28, v253, 8
	v_readlane_b32 s30, v253, 10
	v_readlane_b32 s31, v253, 11
	s_add_u32 s59, s30, s20
	s_mul_i32 s18, s22, 0xfffffd80
	s_waitcnt lgkmcnt(4)
	v_mfma_f32_16x16x32_bf16 v[46:49], v[46:49], v[186:189], 0
	s_mul_i32 s19, s22, 0xfffec000
	s_addc_u32 s60, s31, s21
	s_add_i32 s18, s23, s18
	s_waitcnt lgkmcnt(2)
	v_mfma_f32_16x16x32_bf16 v[194:197], v[50:53], v[190:193], v[46:49]
	s_add_i32 s19, s48, s19
	s_and_b32 s57, s22, 7
	s_and_b32 s19, s19, 0xfffff800
	ds_read_b128 v[46:49], v140 offset:23040
	s_waitcnt lgkmcnt(2)
	v_mfma_f32_16x16x32_bf16 v[50:53], v[54:57], v[186:189], 0
	ds_read_b128 v[54:57], v140 offset:23104
	s_and_b32 s20, s18, 15
	s_add_i32 s21, s18, 0xfffffe00
	s_cmpk_lt_i32 s18, 0x200
	s_cselect_b32 s18, s20, s21
	s_cselect_b32 s20, s50, 0x4000
	s_cselect_b32 s61, s19, 0x10000
	s_cmp_eq_u32 s42, 1
	s_cselect_b32 s19, 4, 16
	s_cselect_b32 s21, 2, 4
	s_cmp_lt_u32 s22, 8
	s_waitcnt lgkmcnt(1)
	v_mfma_f32_16x16x32_bf16 v[46:49], v[46:49], v[186:189], 0
	s_cselect_b32 s22, 1, s19
	s_cselect_b32 s58, 0, s21
	s_add_i32 s19, s22, -1
	s_lshr_b32 s63, s20, s58
	s_and_b32 s62, s19, s18
	s_lshr_b32 s20, s18, s58
	v_readlane_b32 s29, v253, 9
	v_mfma_f32_16x16x32_bf16 v[198:201], v[58:61], v[190:193], v[50:53]
	s_waitcnt lgkmcnt(0)
	v_mfma_f32_16x16x32_bf16 v[202:205], v[54:57], v[190:193], v[46:49]
	s_nop 2
	ds_read_b128 v[46:49], v140 offset:25344
	ds_read_b128 v[50:53], v140 offset:25408
	ds_read_b128 v[54:57], v140 offset:27648
	ds_read_b128 v[58:61], v140 offset:27712
	s_waitcnt lgkmcnt(3)
	v_mfma_f32_16x16x32_bf16 v[46:49], v[46:49], v[186:189], 0
	s_waitcnt lgkmcnt(2)
	v_mfma_f32_16x16x32_bf16 v[206:209], v[50:53], v[190:193], v[46:49]
	ds_read_b128 v[50:53], v140 offset:30016
	s_nop 4
	ds_read_b128 v[46:49], v140 offset:29952
	s_waitcnt lgkmcnt(3)
	v_mfma_f32_16x16x32_bf16 v[54:57], v[54:57], v[186:189], 0
	s_waitcnt lgkmcnt(0)
	v_mfma_f32_16x16x32_bf16 v[46:49], v[46:49], v[186:189], 0
	v_mfma_f32_16x16x32_bf16 v[62:65], v[58:61], v[190:193], v[54:57]
	v_mfma_f32_16x16x32_bf16 v[58:61], v[50:53], v[190:193], v[46:49]
	s_nop 5
	ds_read_b128 v[46:49], v140 offset:32256
	ds_read_b128 v[50:53], v140 offset:32320
	ds_read_b128 v[54:57], v140 offset:34560
	ds_read_b128 v[210:213], v140 offset:34624
	s_waitcnt lgkmcnt(3)
	v_mfma_f32_16x16x32_bf16 v[46:49], v[46:49], v[186:189], 0
	s_waitcnt lgkmcnt(1)
	v_mfma_f32_16x16x32_bf16 v[214:217], v[54:57], v[186:189], 0
	v_mfma_f32_16x16x32_bf16 v[54:57], v[50:53], v[190:193], v[46:49]
	s_nop 4
	ds_read_b128 v[46:49], v140 offset:36864
	s_waitcnt lgkmcnt(1)
	v_mfma_f32_16x16x32_bf16 v[50:53], v[210:213], v[190:193], v[214:217]
	ds_read_b128 v[210:213], v140 offset:36928
	s_waitcnt lgkmcnt(1)
	v_mfma_f32_16x16x32_bf16 v[46:49], v[46:49], v[186:189], 0
	s_waitcnt lgkmcnt(0)
	v_mfma_f32_16x16x32_bf16 v[46:49], v[210:213], v[190:193], v[46:49]
	s_add_i32 s18, s57, 1
	v_cvt_f32_ubyte0_e32 v12, s18
	v_cmp_lt_f32_e32 vcc, s51, v12
	s_and_b64 s[18:19], vcc, exec
	s_cselect_b32 s18, 0xffffffc0, 0
	v_cndmask_b32_e32 v13, 0, v181, vcc
	v_sub_f32_e32 v12, v13, v12
	v_exp_f32_e32 v12, v12
	v_lshl_add_u32 v139, s20, 7, v67
	v_cvt_f32_ubyte0_e32 v13, s22
	v_or_b32_e32 v45, v139, v66
	v_ldexp_f32 v12, v12, s18
	v_mul_f32_e32 v13, v12, v13
	v_add_u32_e32 v12, v45, v143
	v_cmp_gt_u32_e64 s[26:27], s63, v12
	v_add_u32_e32 v12, v45, v144
	v_cmp_gt_u32_e64 s[28:29], s63, v12
	v_add_u32_e32 v12, v45, v145
	v_cmp_gt_u32_e64 s[30:31], s63, v12
	v_add_u32_e32 v12, v45, v146
	v_cmp_gt_u32_e64 s[34:35], s63, v12
	v_add_u32_e32 v12, v45, v174
	v_cmp_gt_u32_e64 s[22:23], s63, v12
	v_add_u32_e32 v12, v45, v175
	v_cmp_gt_u32_e64 s[20:21], s63, v12
	v_add_u32_e32 v12, v45, v176
	v_cmp_gt_u32_e32 vcc, s63, v12
	v_add_u32_e32 v12, v45, v177
	v_cmp_gt_u32_e64 s[18:19], s63, v12
	v_mov_b32_e32 v12, v49
	v_pk_mul_f32 v[12:13], v[12:13], s[44:45]
	v_mul_f32_e32 v186, v68, v194
	v_mul_f32_e32 v187, v69, v13
	s_and_b64 s[26:27], s[24:25], s[26:27]
	v_sub_f32_e32 v49, v186, v187
	v_mul_f32_e32 v186, v70, v195
	v_mul_f32_e32 v187, v71, v13
	v_cndmask_b32_e64 v194, v182, v49, s[26:27]
	v_sub_f32_e32 v49, v186, v187
	s_and_b64 s[26:27], s[4:5], s[28:29]
	v_mul_f32_e32 v186, v72, v196
	v_mul_f32_e32 v187, v73, v13
	v_cndmask_b32_e64 v195, v182, v49, s[26:27]
	v_sub_f32_e32 v186, v186, v187
	s_and_b64 s[26:27], s[6:7], s[30:31]
	v_cndmask_b32_e64 v196, v182, v186, s[26:27]
	v_mul_f32_e32 v186, v74, v197
	v_mul_f32_e32 v187, v75, v13
	s_and_b64 s[26:27], s[8:9], s[34:35]
	v_sub_f32_e32 v186, v186, v187
	v_cndmask_b32_e64 v197, v182, v186, s[26:27]
	v_add_u32_e32 v14, v45, v147
	v_mul_f32_e32 v186, v76, v198
	v_mul_f32_e32 v187, v77, v13
	v_cmp_gt_u32_e64 s[26:27], s63, v14
	v_sub_f32_e32 v186, v186, v187
	s_nop 0
	v_cndmask_b32_e64 v14, v182, v186, s[26:27]
	v_add_u32_e32 v188, v45, v148
	v_mul_f32_e32 v186, v78, v199
	v_mul_f32_e32 v187, v79, v13
	v_cmp_gt_u32_e64 s[26:27], s63, v188
	v_sub_f32_e32 v186, v186, v187
	s_nop 0
	v_cndmask_b32_e64 v188, v182, v186, s[26:27]
	v_add_u32_e32 v189, v45, v149
	v_mul_f32_e32 v186, v80, v200
	v_mul_f32_e32 v187, v81, v13
	v_cmp_gt_u32_e64 s[26:27], s63, v189
	v_sub_f32_e32 v186, v186, v187
	s_nop 0
	v_cndmask_b32_e64 v189, v182, v186, s[26:27]
	v_add_u32_e32 v190, v45, v150
	v_mul_f32_e32 v186, v82, v201
	v_mul_f32_e32 v187, v83, v13
	v_cmp_gt_u32_e64 s[26:27], s63, v190
	v_sub_f32_e32 v186, v186, v187
	s_nop 0
; __device__ void phase_attn(const Params& p, unsigned char* smem, int wave) {
;     ...
;             for (int j = 0; j < 4; ++j) { const int rel = 16 * kt + 4 * gq + j - 64 - ql; const int jk = qi + rel;
;                 const bool relok = (kt == 0) ? (rel >= -64) : ((kt == 8) ? (rel <= 64) : true);
;                 const bool ok = relok && ((unsigned)jk < (unsigned)Ls);
;                 const float v = ok ? sc[kt][j] * 0.18033688011112042f - slope * fabsf((float)rel) : -1e30f;
;                 sc[kt][j] = v; mx = fmaxf(mx, v); }
;         mx = fmaxf(mx, __shfl_xor(mx, 16)); mx = fmaxf(mx, __shfl_xor(mx, 32));
	v_cndmask_b32_e64 v190, v182, v186, s[26:27]
	v_add_u32_e32 v191, v45, v151
	v_mul_f32_e32 v186, v84, v202
	v_mul_f32_e32 v187, v85, v13
	v_cmp_gt_u32_e64 s[26:27], s63, v191
	v_sub_f32_e32 v186, v186, v187
	s_nop 0
	v_cndmask_b32_e64 v191, v182, v186, s[26:27]
	v_add_u32_e32 v192, v45, v152
	v_mul_f32_e32 v186, v86, v203
	v_mul_f32_e32 v187, v87, v13
	v_cmp_gt_u32_e64 s[26:27], s63, v192
	v_sub_f32_e32 v186, v186, v187
	s_nop 0
	v_cndmask_b32_e64 v192, v182, v186, s[26:27]
	v_add_u32_e32 v193, v45, v153
	v_mul_f32_e32 v186, v88, v204
	v_mul_f32_e32 v187, v89, v13
	v_cmp_gt_u32_e64 s[26:27], s63, v193
	v_sub_f32_e32 v186, v186, v187
	s_nop 0
	v_cndmask_b32_e64 v193, v182, v186, s[26:27]
	v_add_u32_e32 v210, v45, v154
	v_mul_f32_e32 v186, v90, v205
	v_mul_f32_e32 v187, v91, v13
	v_cmp_gt_u32_e64 s[26:27], s63, v210
	v_sub_f32_e32 v186, v186, v187
	s_nop 0
	v_cndmask_b32_e64 v198, v182, v186, s[26:27]
	v_add_u32_e32 v211, v45, v155
	v_mul_f32_e32 v186, v92, v206
	v_mul_f32_e32 v187, v93, v13
	v_cmp_gt_u32_e64 s[26:27], s63, v211
	v_sub_f32_e32 v186, v186, v187
	s_nop 0
	v_cndmask_b32_e64 v199, v182, v186, s[26:27]
	v_add_u32_e32 v212, v45, v156
	v_mul_f32_e32 v186, v94, v207
	v_mul_f32_e32 v187, v95, v13
	v_cmp_gt_u32_e64 s[26:27], s63, v212
	v_sub_f32_e32 v186, v186, v187
	s_nop 0
	v_cndmask_b32_e64 v200, v182, v186, s[26:27]
	v_add_u32_e32 v213, v45, v157
	v_mul_f32_e32 v186, v96, v208
	v_mul_f32_e32 v187, v97, v13
	v_cmp_gt_u32_e64 s[26:27], s63, v213
	v_sub_f32_e32 v186, v186, v187
	s_nop 0
	v_cndmask_b32_e64 v201, v182, v186, s[26:27]
	v_add_u32_e32 v214, v45, v158
	v_mul_f32_e32 v186, v98, v209
	v_mul_f32_e32 v187, v99, v13
	v_cmp_gt_u32_e64 s[26:27], s63, v214
	v_sub_f32_e32 v186, v186, v187
	s_nop 0
	v_cndmask_b32_e64 v202, v182, v186, s[26:27]
	v_add_u32_e32 v215, v45, v142
	v_mul_f32_e32 v186, v100, v62
	v_mul_f32_e32 v187, v101, v13
	v_cmp_gt_u32_e64 s[26:27], s63, v215
	v_sub_f32_e32 v62, v186, v187
	v_add_u32_e32 v216, v45, v159
	v_cndmask_b32_e64 v186, v182, v62, s[26:27]
	v_mul_f32_e32 v62, v102, v63
	v_mul_f32_e32 v63, v103, v13
	v_cmp_gt_u32_e64 s[26:27], s63, v216
	v_sub_f32_e32 v62, v62, v63
	s_nop 0
	v_cndmask_b32_e64 v187, v182, v62, s[26:27]
	v_add_u32_e32 v217, v45, v160
	v_mul_f32_e32 v62, v104, v64
	v_mul_f32_e32 v63, v105, v13
	v_cmp_gt_u32_e64 s[26:27], s63, v217
	v_sub_f32_e32 v62, v62, v63
	s_nop 0
	v_cndmask_b32_e64 v64, v182, v62, s[26:27]
	v_add_u32_e32 v218, v45, v161
	v_mul_f32_e32 v62, v106, v65
	v_mul_f32_e32 v63, v107, v13
	v_cmp_gt_u32_e64 s[26:27], s63, v218
	v_sub_f32_e32 v62, v62, v63
	s_nop 0
	v_cndmask_b32_e64 v65, v182, v62, s[26:27]
	v_add_u32_e32 v219, v45, v162
	v_mul_f32_e32 v62, v108, v58
	v_mul_f32_e32 v63, v109, v13
	v_cmp_gt_u32_e64 s[26:27], s63, v219
	v_sub_f32_e32 v58, v62, v63
	v_add_u32_e32 v220, v45, v163
	v_cndmask_b32_e64 v62, v182, v58, s[26:27]
	v_mul_f32_e32 v58, v110, v59
	v_mul_f32_e32 v59, v111, v13
	v_cmp_gt_u32_e64 s[26:27], s63, v220
	v_sub_f32_e32 v58, v58, v59
	s_nop 0
	v_cndmask_b32_e64 v63, v182, v58, s[26:27]
	v_add_u32_e32 v221, v45, v164
	v_mul_f32_e32 v58, v112, v60
	v_mul_f32_e32 v59, v113, v13
	v_cmp_gt_u32_e64 s[26:27], s63, v221
	v_sub_f32_e32 v58, v58, v59
	s_nop 0
	v_cndmask_b32_e64 v60, v182, v58, s[26:27]
	v_add_u32_e32 v222, v45, v165
	v_mul_f32_e32 v58, v114, v61
	v_mul_f32_e32 v59, v115, v13
	v_cmp_gt_u32_e64 s[26:27], s63, v222
	v_sub_f32_e32 v58, v58, v59
	s_nop 0
	v_cndmask_b32_e64 v61, v182, v58, s[26:27]
	v_add_u32_e32 v223, v45, v166
	v_mul_f32_e32 v58, v116, v54
	v_mul_f32_e32 v59, v117, v13
	v_cmp_gt_u32_e64 s[26:27], s63, v223
	v_sub_f32_e32 v54, v58, v59
	v_add_u32_e32 v224, v45, v167
	v_cndmask_b32_e64 v58, v182, v54, s[26:27]
	v_mul_f32_e32 v54, v118, v55
	v_mul_f32_e32 v55, v119, v13
	v_cmp_gt_u32_e64 s[26:27], s63, v224
	v_sub_f32_e32 v54, v54, v55
	s_nop 0
	v_cndmask_b32_e64 v59, v182, v54, s[26:27]
	v_add_u32_e32 v225, v45, v168
	v_mul_f32_e32 v54, v120, v56
	v_mul_f32_e32 v55, v121, v13
	v_cmp_gt_u32_e64 s[26:27], s63, v225
	v_sub_f32_e32 v54, v54, v55
	s_nop 0
	v_cndmask_b32_e64 v56, v182, v54, s[26:27]
	v_add_u32_e32 v226, v45, v169
	v_mul_f32_e32 v54, v122, v57
	v_mul_f32_e32 v55, v123, v13
	v_cmp_gt_u32_e64 s[26:27], s63, v226
	v_sub_f32_e32 v54, v54, v55
	s_nop 0
	v_cndmask_b32_e64 v57, v182, v54, s[26:27]
	v_add_u32_e32 v227, v45, v170
	v_mul_f32_e32 v54, v124, v50
	v_mul_f32_e32 v55, v125, v13
	v_cmp_gt_u32_e64 s[26:27], s63, v227
	v_sub_f32_e32 v50, v54, v55
	v_max3_f32 v49, v194, s52, v195
	v_cndmask_b32_e64 v54, v182, v50, s[26:27]
	v_add_u32_e32 v228, v45, v171
	v_max3_f32 v49, v49, v196, v197
	v_mul_f32_e32 v50, v126, v51
	v_mul_f32_e32 v51, v127, v13
	v_max3_f32 v49, v49, v14, v188
	v_sub_f32_e32 v50, v50, v51
	v_cmp_gt_u32_e64 s[26:27], s63, v228
	v_max3_f32 v49, v49, v189, v190
	s_nop 0
	v_cndmask_b32_e64 v55, v182, v50, s[26:27]
	v_add_u32_e32 v229, v45, v172
	v_max3_f32 v49, v49, v191, v192
	v_mul_f32_e32 v50, v128, v52
	v_mul_f32_e32 v51, v129, v13
	v_max3_f32 v49, v49, v193, v198
	v_sub_f32_e32 v50, v50, v51
	v_cmp_gt_u32_e64 s[26:27], s63, v229
	v_max3_f32 v49, v49, v199, v200
	s_nop 0
	v_cndmask_b32_e64 v52, v182, v50, s[26:27]
	v_add_u32_e32 v230, v45, v173
	v_max3_f32 v49, v49, v201, v202
	v_mul_f32_e32 v50, v130, v53
	v_mul_f32_e32 v51, v131, v13
	v_max3_f32 v49, v49, v186, v187
	v_sub_f32_e32 v50, v50, v51
	v_cmp_gt_u32_e64 s[26:27], s63, v230
	v_max3_f32 v49, v49, v64, v65
	s_nop 0
	v_cndmask_b32_e64 v53, v182, v50, s[26:27]
	v_max3_f32 v49, v49, v62, v63
	v_mul_f32_e32 v50, v132, v46
	v_mul_f32_e32 v51, v133, v13
	v_max3_f32 v49, v49, v60, v61
	v_sub_f32_e32 v46, v50, v51
	s_and_b64 s[22:23], s[10:11], s[22:23]
	v_max3_f32 v49, v49, v58, v59
	v_cndmask_b32_e64 v50, v182, v46, s[22:23]
	v_max3_f32 v49, v49, v56, v57
	v_mul_f32_e32 v46, v134, v47
	v_mul_f32_e32 v47, v135, v13
	v_max3_f32 v49, v49, v54, v55
	v_sub_f32_e32 v46, v46, v47
	s_and_b64 s[20:21], s[12:13], s[20:21]
	v_max3_f32 v49, v49, v52, v53
	v_cndmask_b32_e64 v51, v182, v46, s[20:21]
	v_max3_f32 v203, v49, v50, v51
	v_mov_b32_e32 v49, v13
	v_pk_mul_f32 v[46:47], v[48:49], v[136:137]
	s_and_b64 vcc, s[14:15], vcc
	v_sub_f32_e32 v46, v46, v47
	v_and_b32_e32 v206, 64, v183
	v_cndmask_b32_e32 v47, v182, v46, vcc
	v_fma_f32 v12, -v13, v178, v12
	s_and_b64 vcc, s[16:17], s[18:19]
	v_xor_b32_e32 v46, 16, v183
	v_add_u32_e32 v48, 64, v206
	v_cndmask_b32_e32 v12, v182, v12, vcc
	v_cmp_lt_i32_e32 vcc, v46, v48
	v_max3_f32 v13, v203, v47, v12
	s_nop 0
	v_cndmask_b32_e32 v46, v183, v46, vcc
	v_lshlrev_b32_e32 v203, 2, v46
	ds_bpermute_b32 v46, v203, v13
	s_waitcnt lgkmcnt(0)
; __device__ __forceinline__ unsigned cvtpk(float lo, float hi) { const f32v2_t v = {lo, hi}; const bf16v2_t b = __builtin_convertvector(v, bf16v2_t); return __builtin_bit_cast(unsigned, b); }
; __device__ __forceinline__ v4i16_t lds_tr16(const bf16_t* p) { return __builtin_amdgcn_ds_read_tr16_b64_v4i16((LAS v4i16_t*)p); }
; __device__ void phase_attn(const Params& p, unsigned char* smem, int wave) {
;     ...
;         mx = fmaxf(mx, __shfl_xor(mx, 16)); mx = fmaxf(mx, __shfl_xor(mx, 32));
;         float den = 0.f;
; #pragma unroll
;         for (int kt = 0; kt < 9; ++kt)
; #pragma unroll
;             for (int j = 0; j < 4; ++j) { const float pv = __builtin_amdgcn_exp2f(sc[kt][j] - mx); sc[kt][j] = pv; den += pv; }
;         sc[9] = (f32x4){0.f, 0.f, 0.f, 0.f};
;         den += __shfl_xor(den, 16); den += __shfl_xor(den, 32);
;         f32x4 oacc[4];
; #pragma unroll
;         for (int et = 0; et < 4; ++et) oacc[et] = (f32x4){0.f, 0.f, 0.f, 0.f};
; #pragma unroll
;         for (int ks = 0; ks < 5; ++ks) {
;             u32x4 pu; pu.x = cvtpk(sc[2 * ks][0], sc[2 * ks][1]); pu.y = cvtpk(sc[2 * ks][2], sc[2 * ks][3]); pu.z = cvtpk(sc[2 * ks + 1][0], sc[2 * ks + 1][1]); pu.w = cvtpk(sc[2 * ks + 1][2], sc[2 * ks + 1][3]);
;             const bf16x8 pf = __builtin_bit_cast(bf16x8, pu);
;             const bf16_t* vrow = Vs + (16 * w4 + 32 * ks + 4 * gq + (ql >> 2)) * ATT_LD + 4 * (ql & 3);
; #pragma unroll
;             for (int et = 0; et < 4; ++et) {
;                 const v4i16_t t0 = lds_tr16(vrow + 16 * et);
;                 v4i16_t t1 = (v4i16_t){0, 0, 0, 0};
;                 if (ks < 4) t1 = lds_tr16(vrow + 16 * ATT_LD + 16 * et);
;                 const bf16x8 vf = __builtin_shufflevector(t0, t1, 0, 1, 2, 3, 4, 5, 6, 7);
;                 oacc[et] = __builtin_amdgcn_mfma_f32_16x16x32_bf16(pf, vf, oacc[et], 0, 0, 0); }
	v_max_f32_e32 v46, v46, v46
	v_max_f32_e32 v13, v13, v46
	v_xor_b32_e32 v46, 32, v183
	v_cmp_lt_i32_e32 vcc, v46, v48
	s_nop 1
	v_cndmask_b32_e32 v46, v183, v46, vcc
	v_lshlrev_b32_e32 v204, 2, v46
	ds_bpermute_b32 v46, v204, v13
	s_waitcnt lgkmcnt(0)
	v_max_f32_e32 v46, v46, v46
	v_max_f32_e32 v46, v13, v46
	v_sub_f32_e32 v13, v194, v46
	v_exp_f32_e32 v13, v13
	v_sub_f32_e32 v49, v195, v46
	v_exp_f32_e32 v49, v49
	v_sub_f32_e32 v194, v196, v46
	v_exp_f32_e32 v194, v194
	v_sub_f32_e32 v195, v197, v46
	v_exp_f32_e32 v195, v195
	v_sub_f32_e32 v14, v14, v46
	v_add_f32_e32 v48, 0, v13
	v_exp_f32_e32 v14, v14
	v_sub_f32_e32 v188, v188, v46
	v_add_f32_e32 v48, v49, v48
	v_exp_f32_e32 v188, v188
	v_sub_f32_e32 v189, v189, v46
	v_add_f32_e32 v48, v194, v48
	v_exp_f32_e32 v189, v189
	v_sub_f32_e32 v190, v190, v46
	v_add_f32_e32 v48, v195, v48
	v_exp_f32_e32 v190, v190
	v_sub_f32_e32 v191, v191, v46
	v_add_f32_e32 v48, v14, v48
	v_exp_f32_e32 v191, v191
	v_sub_f32_e32 v192, v192, v46
	v_add_f32_e32 v48, v188, v48
	v_exp_f32_e32 v192, v192
	v_sub_f32_e32 v193, v193, v46
	v_add_f32_e32 v48, v189, v48
	v_exp_f32_e32 v193, v193
	v_sub_f32_e32 v196, v198, v46
	v_add_f32_e32 v48, v190, v48
	v_exp_f32_e32 v196, v196
	v_sub_f32_e32 v197, v199, v46
	v_add_f32_e32 v48, v191, v48
	v_exp_f32_e32 v197, v197
	v_sub_f32_e32 v198, v200, v46
	v_add_f32_e32 v48, v192, v48
	v_exp_f32_e32 v198, v198
	v_sub_f32_e32 v199, v201, v46
	v_add_f32_e32 v48, v193, v48
	v_exp_f32_e32 v199, v199
	v_sub_f32_e32 v200, v202, v46
	v_add_f32_e32 v48, v196, v48
	v_exp_f32_e32 v200, v200
	v_sub_f32_e32 v186, v186, v46
	v_add_f32_e32 v48, v197, v48
	v_exp_f32_e32 v207, v186
	v_sub_f32_e32 v186, v187, v46
	v_add_f32_e32 v48, v198, v48
	v_exp_f32_e32 v208, v186
	v_sub_f32_e32 v64, v64, v46
	v_add_f32_e32 v48, v199, v48
	v_exp_f32_e32 v64, v64
	v_sub_f32_e32 v65, v65, v46
	v_add_f32_e32 v48, v200, v48
	v_exp_f32_e32 v65, v65
	v_sub_f32_e32 v62, v62, v46
	v_add_f32_e32 v48, v207, v48
	v_exp_f32_e32 v209, v62
	v_sub_f32_e32 v62, v63, v46
	v_add_f32_e32 v48, v208, v48
	v_exp_f32_e32 v210, v62
	v_sub_f32_e32 v60, v60, v46
	v_add_f32_e32 v48, v64, v48
	v_exp_f32_e32 v211, v60
	v_sub_f32_e32 v60, v61, v46
	v_add_f32_e32 v48, v65, v48
	v_exp_f32_e32 v212, v60
	v_sub_f32_e32 v58, v58, v46
	v_add_f32_e32 v48, v209, v48
	v_exp_f32_e32 v213, v58
	v_sub_f32_e32 v58, v59, v46
	v_add_f32_e32 v48, v210, v48
	v_exp_f32_e32 v214, v58
	v_sub_f32_e32 v56, v56, v46
	v_add_f32_e32 v48, v211, v48
	v_exp_f32_e32 v215, v56
	v_sub_f32_e32 v56, v57, v46
	v_add_f32_e32 v48, v212, v48
	v_exp_f32_e32 v216, v56
	v_sub_f32_e32 v54, v54, v46
	v_add_f32_e32 v48, v213, v48
	v_exp_f32_e32 v217, v54
	v_sub_f32_e32 v54, v55, v46
	v_add_f32_e32 v48, v214, v48
	v_exp_f32_e32 v218, v54
	v_sub_f32_e32 v52, v52, v46
	v_add_f32_e32 v48, v215, v48
	v_exp_f32_e32 v219, v52
	v_sub_f32_e32 v52, v53, v46
	v_add_f32_e32 v48, v216, v48
	v_exp_f32_e32 v220, v52
	v_sub_f32_e32 v50, v50, v46
	v_add_f32_e32 v48, v217, v48
	v_exp_f32_e32 v221, v50
	v_add_f32_e32 v48, v218, v48
	v_add_f32_e32 v48, v219, v48
	v_add_f32_e32 v48, v220, v48
	v_add_f32_e32 v201, v221, v48
	v_sub_f32_e32 v48, v51, v46
	v_exp_f32_e32 v222, v48
	v_sub_f32_e32 v47, v47, v46
	v_cvt_pk_bf16_f32 v48, v13, v49
	v_exp_f32_e32 v13, v47
	v_sub_f32_e32 v12, v12, v46
	v_cvt_pk_bf16_f32 v50, v14, v188
	v_exp_f32_e32 v14, v12
	v_add_f32_e32 v12, v222, v201
	v_add_f32_e32 v12, v13, v12
	v_cvt_pk_bf16_f32 v49, v194, v195
	v_add_f32_e32 v12, v14, v12
	ds_bpermute_b32 v47, v203, v12
	v_cvt_pk_bf16_f32 v51, v189, v190
	ds_read_b64_tr_b16 v[54:55], v179 offset:57600
	ds_read_b64_tr_b16 v[52:53], v179 offset:55296
	ds_read_b64_tr_b16 v[56:57], v179 offset:55328
	ds_read_b64_tr_b16 v[60:61], v179 offset:55360
	ds_read_b64_tr_b16 v[186:187], v179 offset:55392
	ds_read_b64_tr_b16 v[58:59], v179 offset:57632
	ds_read_b64_tr_b16 v[62:63], v179 offset:57664
	ds_read_b64_tr_b16 v[188:189], v179 offset:57696
	v_cvt_pk_bf16_f32 v248, v191, v192
	v_cvt_pk_bf16_f32 v249, v193, v196
	v_cvt_pk_bf16_f32 v250, v197, v198
	v_cvt_pk_bf16_f32 v251, v199, v200
	ds_read_b64_tr_b16 v[234:235], v179 offset:62208
	ds_read_b64_tr_b16 v[232:233], v179 offset:59904
	ds_read_b64_tr_b16 v[236:237], v179 offset:59936
	ds_read_b64_tr_b16 v[240:241], v179 offset:59968
	ds_read_b64_tr_b16 v[244:245], v179 offset:60000
	ds_read_b64_tr_b16 v[238:239], v179 offset:62240
	s_waitcnt lgkmcnt(12)
	v_mfma_f32_16x16x32_bf16 v[52:55], v[48:51], v[52:55], 0
	ds_read_b64_tr_b16 v[242:243], v179 offset:62272
	ds_read_b64_tr_b16 v[246:247], v179 offset:62304
	v_add_f32_e32 v47, v12, v47
	ds_bpermute_b32 v223, v204, v47
	s_waitcnt lgkmcnt(11)
	v_mfma_f32_16x16x32_bf16 v[56:59], v[48:51], v[56:59], 0
	s_waitcnt lgkmcnt(10)
	v_mfma_f32_16x16x32_bf16 v[60:63], v[48:51], v[60:63], 0
	s_waitcnt lgkmcnt(9)
	v_mfma_f32_16x16x32_bf16 v[48:51], v[48:51], v[186:189], 0
	v_cvt_pk_bf16_f32 v186, v207, v208
	v_cvt_pk_bf16_f32 v187, v64, v65
	v_cvt_pk_bf16_f32 v188, v209, v210
	v_cvt_pk_bf16_f32 v189, v211, v212
	ds_read_b64_tr_b16 v[192:193], v180 offset:11520
	ds_read_b64_tr_b16 v[190:191], v179 offset:64512
	ds_read_b64_tr_b16 v[194:195], v179 offset:64544
	ds_read_b64_tr_b16 v[198:199], v179 offset:64576
	ds_read_b64_tr_b16 v[202:203], v179 offset:64608
	ds_read_b64_tr_b16 v[196:197], v180 offset:11552
	s_waitcnt lgkmcnt(13)
	v_mfma_f32_16x16x32_bf16 v[52:55], v[248:251], v[232:235], v[52:55]
	ds_read_b64_tr_b16 v[200:201], v180 offset:11584
	ds_read_b64_tr_b16 v[204:205], v180 offset:11616
	s_waitcnt lgkmcnt(11)
	v_mfma_f32_16x16x32_bf16 v[56:59], v[248:251], v[236:239], v[56:59]
	s_waitcnt lgkmcnt(10)
; __device__ __forceinline__ unsigned cvtpk(float lo, float hi) { const f32v2_t v = {lo, hi}; const bf16v2_t b = __builtin_convertvector(v, bf16v2_t); return __builtin_bit_cast(unsigned, b); }
; __device__ __forceinline__ bf16_t f2bf(float f) { return (bf16_t)cvtpk(f, 0.f); }
; __device__ __forceinline__ v4i16_t lds_tr16(const bf16_t* p) { return __builtin_amdgcn_ds_read_tr16_b64_v4i16((LAS v4i16_t*)p); }
; __device__ void phase_attn(const Params& p, unsigned char* smem, int wave) {
;     ...
; #pragma unroll
;         for (int ks = 0; ks < 5; ++ks) {
;             u32x4 pu; pu.x = cvtpk(sc[2 * ks][0], sc[2 * ks][1]); pu.y = cvtpk(sc[2 * ks][2], sc[2 * ks][3]); pu.z = cvtpk(sc[2 * ks + 1][0], sc[2 * ks + 1][1]); pu.w = cvtpk(sc[2 * ks + 1][2], sc[2 * ks + 1][3]);
;             const bf16x8 pf = __builtin_bit_cast(bf16x8, pu);
;             const bf16_t* vrow = Vs + (16 * w4 + 32 * ks + 4 * gq + (ql >> 2)) * ATT_LD + 4 * (ql & 3);
; #pragma unroll
;             for (int et = 0; et < 4; ++et) {
;                 const v4i16_t t0 = lds_tr16(vrow + 16 * et);
;                 v4i16_t t1 = (v4i16_t){0, 0, 0, 0};
;                 if (ks < 4) t1 = lds_tr16(vrow + 16 * ATT_LD + 16 * et);
;                 const bf16x8 vf = __builtin_shufflevector(t0, t1, 0, 1, 2, 3, 4, 5, 6, 7);
;                 oacc[et] = __builtin_amdgcn_mfma_f32_16x16x32_bf16(pf, vf, oacc[et], 0, 0, 0); }
;             __builtin_amdgcn_sched_barrier(0);
;         }
; #pragma unroll
;         for (int j = 0; j < 4; ++j) { const float dq = __shfl(den, 4 * gq + j); const float inv = __builtin_amdgcn_rcpf(dq);
;             const int tok = gbase + (i0 + 16 * w4 + 4 * gq + j) * d + res;
; #pragma unroll
;             for (int et = 0; et < 4; ++et) ato[(size_t)tok * 512 + h * 64 + 16 * et + ql] = f2bf(oacc[et][j] * inv); }
;         if (gq == 0) { const int tok = gbase + qi * d + res; lse[((size_t)br * NTOK + tok) * 8 + h] = mx * 0.6931471805599453f + __logf(den); }
	v_mfma_f32_16x16x32_bf16 v[60:63], v[248:251], v[240:243], v[60:63]
	s_waitcnt lgkmcnt(9)
	v_mfma_f32_16x16x32_bf16 v[48:51], v[248:251], v[244:247], v[48:51]
	v_cvt_pk_bf16_f32 v248, v213, v214
	v_cvt_pk_bf16_f32 v249, v215, v216
	v_cvt_pk_bf16_f32 v250, v217, v218
	v_cvt_pk_bf16_f32 v251, v219, v220
	ds_read_b64_tr_b16 v[234:235], v180 offset:16128
	ds_read_b64_tr_b16 v[232:233], v180 offset:13824
	ds_read_b64_tr_b16 v[236:237], v180 offset:13856
	ds_read_b64_tr_b16 v[240:241], v180 offset:13888
	ds_read_b64_tr_b16 v[244:245], v180 offset:13920
	ds_read_b64_tr_b16 v[238:239], v180 offset:16160
	s_waitcnt lgkmcnt(12)
	v_mfma_f32_16x16x32_bf16 v[52:55], v[186:189], v[190:193], v[52:55]
	ds_read_b64_tr_b16 v[242:243], v180 offset:16192
	ds_read_b64_tr_b16 v[246:247], v180 offset:16224
	s_waitcnt lgkmcnt(10)
	v_mfma_f32_16x16x32_bf16 v[56:59], v[186:189], v[194:197], v[56:59]
	s_waitcnt lgkmcnt(9)
	v_mfma_f32_16x16x32_bf16 v[60:63], v[186:189], v[198:201], v[60:63]
	s_waitcnt lgkmcnt(8)
	v_mfma_f32_16x16x32_bf16 v[48:51], v[186:189], v[202:205], v[48:51]
	v_cvt_pk_bf16_f32 v12, v221, v222
	v_cvt_pk_bf16_f32 v13, v13, v14
	v_mov_b32_e32 v14, v15
	ds_read_b64_tr_b16 v[186:187], v180 offset:18432
	ds_read_b64_tr_b16 v[190:191], v180 offset:18464
	ds_read_b64_tr_b16 v[194:195], v180 offset:18496
	ds_read_b64_tr_b16 v[198:199], v180 offset:18528
	v_mov_b32_e32 v188, v15
	v_mov_b32_e32 v189, v15
	v_mov_b32_e32 v192, v15
	v_mov_b32_e32 v193, v15
	v_mov_b32_e32 v196, v15
	v_mov_b32_e32 v197, v15
	v_mov_b32_e32 v200, v15
	v_mov_b32_e32 v201, v15
	s_waitcnt lgkmcnt(10)
	v_mfma_f32_16x16x32_bf16 v[52:55], v[248:251], v[232:235], v[52:55]
	s_waitcnt lgkmcnt(6)
	v_mfma_f32_16x16x32_bf16 v[56:59], v[248:251], v[236:239], v[56:59]
	s_waitcnt lgkmcnt(5)
	v_mfma_f32_16x16x32_bf16 v[60:63], v[248:251], v[240:243], v[60:63]
	s_waitcnt lgkmcnt(4)
	v_mfma_f32_16x16x32_bf16 v[48:51], v[248:251], v[244:247], v[48:51]
	s_waitcnt lgkmcnt(3)
	v_mfma_f32_16x16x32_bf16 v[52:55], v[12:15], v[186:189], v[52:55]
	s_waitcnt lgkmcnt(2)
	v_mfma_f32_16x16x32_bf16 v[56:59], v[12:15], v[190:193], v[56:59]
	s_waitcnt lgkmcnt(1)
	v_mfma_f32_16x16x32_bf16 v[60:63], v[12:15], v[194:197], v[60:63]
	s_waitcnt lgkmcnt(0)
	v_mfma_f32_16x16x32_bf16 v[48:51], v[12:15], v[198:201], v[48:51]
	v_or_b32_e32 v14, v206, v141
	v_add_f32_e32 v12, v47, v223
	v_lshlrev_b32_e32 v14, 2, v14
	ds_bpermute_b32 v47, v14, v12
	s_add_i32 s62, s62, s61
	s_lshl_b32 s18, s57, 7
	s_add_u32 s18, s59, s18
	v_or_b32_e32 v13, v139, v141
	s_addc_u32 s19, s60, 0
	v_mov_b32_e32 v139, v15
	s_waitcnt lgkmcnt(0)
	v_rcp_f32_e32 v47, v47
	v_lshl_add_u64 v[64:65], s[18:19], 0, v[138:139]
	v_lshlrev_b32_e32 v139, s58, v13
	v_add_u32_e32 v186, s62, v139
	v_ashrrev_i32_e32 v187, 31, v186
	v_lshlrev_b64 v[186:187], 10, v[186:187]
	v_mul_f32_e32 v52, v52, v47
	v_lshl_add_u64 v[186:187], v[64:65], 0, v[186:187]
	v_cvt_pk_bf16_f32 v52, v52, s0
	global_store_short v[186:187], v52, off
	v_mul_f32_e32 v52, v56, v47
	ds_bpermute_b32 v56, v14, v12 offset:4
	v_cvt_pk_bf16_f32 v52, v52, s0
	global_store_short v[186:187], v52, off offset:32
	v_mul_f32_e32 v52, v60, v47
	v_mul_f32_e32 v47, v48, v47
	v_cvt_pk_bf16_f32 v47, v47, s0
	global_store_short v[186:187], v47, off offset:96
	s_waitcnt lgkmcnt(0)
	v_rcp_f32_e32 v47, v56
	v_or_b32_e32 v48, 1, v13
	v_cvt_pk_bf16_f32 v52, v52, s0
	v_lshlrev_b32_e32 v48, s58, v48
	global_store_short v[186:187], v52, off offset:64
	v_add_u32_e32 v186, s62, v48
	v_ashrrev_i32_e32 v187, 31, v186
	v_lshlrev_b64 v[186:187], 10, v[186:187]
	v_mul_f32_e32 v48, v53, v47
	v_lshl_add_u64 v[186:187], v[64:65], 0, v[186:187]
	v_cvt_pk_bf16_f32 v48, v48, s0
	ds_bpermute_b32 v52, v14, v12 offset:8
	global_store_short v[186:187], v48, off
	v_mul_f32_e32 v48, v57, v47
	v_cvt_pk_bf16_f32 v48, v48, s0
	global_store_short v[186:187], v48, off offset:32
	v_mul_f32_e32 v48, v61, v47
	v_mul_f32_e32 v47, v49, v47
	v_cvt_pk_bf16_f32 v48, v48, s0
	v_cvt_pk_bf16_f32 v47, v47, s0
	global_store_short v[186:187], v48, off offset:64
	global_store_short v[186:187], v47, off offset:96
	s_waitcnt lgkmcnt(0)
	v_rcp_f32_e32 v47, v52
	v_or_b32_e32 v48, 2, v13
	v_lshlrev_b32_e32 v48, s58, v48
	v_add_u32_e32 v48, s62, v48
	v_or_b32_e32 v14, 12, v14
	v_ashrrev_i32_e32 v49, 31, v48
	ds_bpermute_b32 v14, v14, v12
	v_lshlrev_b64 v[48:49], 10, v[48:49]
	v_mul_f32_e32 v52, v54, v47
	v_lshl_add_u64 v[48:49], v[64:65], 0, v[48:49]
	v_cvt_pk_bf16_f32 v52, v52, s0
	global_store_short v[48:49], v52, off
	v_mul_f32_e32 v52, v58, v47
	v_cvt_pk_bf16_f32 v52, v52, s0
	global_store_short v[48:49], v52, off offset:32
	v_mul_f32_e32 v52, v62, v47
	v_mul_f32_e32 v47, v50, v47
	s_waitcnt lgkmcnt(0)
	v_rcp_f32_e32 v14, v14
	v_or_b32_e32 v13, 3, v13
	v_cvt_pk_bf16_f32 v52, v52, s0
	v_cvt_pk_bf16_f32 v47, v47, s0
	v_lshlrev_b32_e32 v13, s58, v13
	global_store_short v[48:49], v52, off offset:64
	global_store_short v[48:49], v47, off offset:96
	v_add_u32_e32 v48, s62, v13
	v_ashrrev_i32_e32 v49, 31, v48
	v_lshlrev_b64 v[48:49], 10, v[48:49]
	v_mul_f32_e32 v13, v55, v14
	v_lshl_add_u64 v[48:49], v[64:65], 0, v[48:49]
	v_cvt_pk_bf16_f32 v13, v13, s0
	global_store_short v[48:49], v13, off
	v_mul_f32_e32 v13, v59, v14
	v_cvt_pk_bf16_f32 v13, v13, s0
	global_store_short v[48:49], v13, off offset:32
	v_mul_f32_e32 v13, v63, v14
	v_cvt_pk_bf16_f32 v13, v13, s0
	global_store_short v[48:49], v13, off offset:64
	v_mul_f32_e32 v13, v51, v14
	v_cvt_pk_bf16_f32 v13, v13, s0
	global_store_short v[48:49], v13, off offset:96
	s_and_saveexec_b64 s[20:21], s[0:1]
	s_cbranch_execz .LBB0_719
	v_cmp_gt_f32_e32 vcc, s53, v12
	s_nop 1
	v_cndmask_b32_e64 v13, 0, 32, vcc
	v_ldexp_f32 v12, v12, v13
	v_log_f32_e32 v13, v12
	v_lshlrev_b32_e32 v12, s58, v45
	v_add_u32_e32 v12, s62, v12
	v_mul_f32_e32 v14, 0x3f317217, v13
	v_fma_f32 v14, v13, s54, -v14
	v_fmac_f32_e32 v14, 0x3377d1cf, v13
	v_fmac_f32_e32 v14, 0x3f317217, v13
	v_cmp_lt_f32_e64 s[18:19], |v13|, s55
	s_nop 1
	v_cndmask_b32_e64 v13, v13, v14, s[18:19]
	v_cndmask_b32_e32 v14, 0, v184, vcc
	v_sub_f32_e32 v14, v13, v14
	v_ashrrev_i32_e32 v13, 31, v12
	v_mad_i64_i32 v[12:13], s[18:19], s42, v185, v[12:13]
	v_lshlrev_b64 v[12:13], 5, v[12:13]
	v_lshl_add_u64 v[12:13], s[40:41], 0, v[12:13]
	s_lshl_b32 s42, s57, 2
	v_fmac_f32_e32 v14, 0x3f317218, v46
	v_lshl_add_u64 v[12:13], v[12:13], 0, s[42:43]
	global_store_dword v[12:13], v14, off
	s_branch .LBB0_719
